# instruction trimming in the issue-bound HGRN scan loop: 24 dead phi-copy v_mov removed (bit-identical) on top of v40
# speedup vs baseline: 1.0007x; 1.0007x over previous
; #define LAS __attribute__((address_space(3)))
; DI void hgrn_scan(ldsp lds, const bf16_t* QT, const bf16_t* KT, const bf16_t* KHT, const bf16_t* HVT, const float* DEC, bf16_t* HO, int vcu, int G) {
;     ...
;             ldsp qb_ = Lb + HS_QT + (tb * 32 + l31) * HS_QP + db * 64 + hh * 16; ldsp kb_ = Lb + HS_KT + l31 * HS_QP + db * 64 + hh * 16;
;             ldsp qr_ = Lb + HS_QT + (tb * 32 + l31) * HS_QP + 8 * hh + db * 64; ldsp vr_ = Lb + HS_VT + l31 * HS_P + 8 * hh;
;             const bf16x8 qv0 = *(const LAS bf16x8*)(qb_), qv1 = *(const LAS bf16x8*)(qb_ + 32), k00 = *(const LAS bf16x8*)(kb_), k01 = *(const LAS bf16x8*)(kb_ + 32);
;             const bf16x8 qa0 = lds_8x2(qr_, 16), qa1 = lds_8x2(qr_ + 32, 16), v00 = lds_8x2(vr_, 16), v01 = lds_8x2(vr_ + 32, 16);
;             bf16x8 k10 = k00, k11 = k01, v10 = v00, v11 = v01;
;             if (tb == 1) { k10 = *(const LAS bf16x8*)(kb_ + 32 * HS_QP); k11 = *(const LAS bf16x8*)(kb_ + 32 * HS_QP + 32); v10 = lds_8x2(vr_ + 64, 16); v11 = lds_8x2(vr_ + 96, 16); }
.LBB0_2075:
	s_or_b64 exec, exec, s[8:9]
	v_add_u32_e32 v28, v174, v147
	v_add_u32_e32 v28, 0xc800, v28
	ds_read_b128 v[88:91], v223
	ds_read_b128 v[84:87], v223 offset:32
	ds_read_b128 v[24:27], v224 offset:17408
	ds_read_b128 v[20:23], v224 offset:17440
	ds_read2_b64 v[16:19], v225 offset1:2
	ds_read2_b64 v[112:115], v225 offset0:4 offset1:6
	ds_read2_b64 v[108:111], v28 offset0:128 offset1:130
	ds_read2_b64 v[96:99], v28 offset0:132 offset1:134
	v_cndmask_b32_e64 v29, 0, 1, s[80:81]
	s_waitcnt lgkmcnt(4)
	v_cmp_ne_u32_e64 s[8:9], 1, v29
	s_andn2_b64 vcc, exec, s[80:81]
	s_waitcnt lgkmcnt(0)
	s_cbranch_vccnz .LBB0_2077
	ds_read_b128 v[104:107], v224 offset:26112
	ds_read_b128 v[100:103], v224 offset:26144
	ds_read2_b64 v[92:95], v28 offset0:136 offset1:138
	ds_read2_b64 v[80:83], v28 offset0:140 offset1:142

; #define LAS __attribute__((address_space(3)))
; DI void hgrn_scan(ldsp lds, const bf16_t* QT, const bf16_t* KT, const bf16_t* KHT, const bf16_t* HVT, const float* DEC, bf16_t* HO, int vcu, int G) {
;     ...
;             ldsp qb_ = Lb + HS_QT + (tb * 32 + l31) * HS_QP + db * 64 + hh * 16; ldsp kb_ = Lb + HS_KT + l31 * HS_QP + db * 64 + hh * 16;
;             ldsp qr_ = Lb + HS_QT + (tb * 32 + l31) * HS_QP + 8 * hh + db * 64; ldsp vr_ = Lb + HS_VT + l31 * HS_P + 8 * hh;
;             const bf16x8 qv0 = *(const LAS bf16x8*)(qb_), qv1 = *(const LAS bf16x8*)(qb_ + 32), k00 = *(const LAS bf16x8*)(kb_), k01 = *(const LAS bf16x8*)(kb_ + 32);
;             const bf16x8 qa0 = lds_8x2(qr_, 16), qa1 = lds_8x2(qr_ + 32, 16), v00 = lds_8x2(vr_, 16), v01 = lds_8x2(vr_ + 32, 16);
;             bf16x8 k10 = k00, k11 = k01, v10 = v00, v11 = v01;
;             if (tb == 1) { k10 = *(const LAS bf16x8*)(kb_ + 32 * HS_QP); k11 = *(const LAS bf16x8*)(kb_ + 32 * HS_QP + 32); v10 = lds_8x2(vr_ + 64, 16); v11 = lds_8x2(vr_ + 96, 16); }
.LBB0_2093:
	v_add_u32_e32 v28, 0xe000, v225
	ds_read_b128 v[88:91], v223 offset:57344
	ds_read_b128 v[84:87], v223 offset:57376
	ds_read_b128 v[24:27], v227
	ds_read_b128 v[20:23], v227 offset:32
	ds_read2_b64 v[16:19], v28 offset1:2
	ds_read2_b64 v[112:115], v28 offset0:4 offset1:6
	v_add_u32_e32 v28, v176, v147
	ds_read2_b64 v[108:111], v28 offset1:2
	ds_read2_b64 v[96:99], v28 offset0:4 offset1:6
	s_waitcnt lgkmcnt(5)
	s_waitcnt lgkmcnt(4)
	s_and_b64 vcc, exec, s[8:9]
	s_waitcnt lgkmcnt(1)
	s_waitcnt lgkmcnt(0)
	s_cbranch_vccnz .LBB0_2095
	ds_read_b128 v[100:103], v227 offset:8704
	ds_read_b128 v[104:107], v227 offset:8736
	ds_read2_b64 v[92:95], v28 offset0:8 offset1:10
	ds_read2_b64 v[80:83], v28 offset0:12 offset1:14
